# attention online softmax: accumulator rescale only when a row max grows by more than 8 in the log2 domain (running max may lag; softmax is shift-invariant, same f32/bf16 kinds)
# speedup vs baseline: 1.0227x; 1.0117x over previous
.LBB0_685:
	v_lshl_or_b32 v0, s38, 5, v202
	v_mad_u32_u24 v0, v0, s30, v208
	ds_read_b128 v[2:5], v0
	ds_read_b128 v[6:9], v0 offset:32
	s_waitcnt lgkmcnt(1)
	v_mfma_f32_32x32x16_bf16 v[80:95], v[2:5], v[148:151], 0
	s_waitcnt lgkmcnt(0)
	v_mfma_f32_32x32x16_bf16 v[80:95], v[6:9], v[96:99], v[80:95]
	ds_read_b128 v[2:5], v0 offset:64
	ds_read_b128 v[6:9], v0 offset:96
	s_waitcnt lgkmcnt(1)
	v_mfma_f32_32x32x16_bf16 v[80:95], v[2:5], v[100:103], v[80:95]
	s_waitcnt lgkmcnt(0)
	v_mfma_f32_32x32x16_bf16 v[80:95], v[6:9], v[104:107], v[80:95]
	ds_read_b128 v[2:5], v0 offset:128
	ds_read_b128 v[6:9], v0 offset:160
	s_waitcnt lgkmcnt(1)
	v_mfma_f32_32x32x16_bf16 v[80:95], v[2:5], v[108:111], v[80:95]
	s_waitcnt lgkmcnt(0)
	v_mfma_f32_32x32x16_bf16 v[80:95], v[6:9], v[112:115], v[80:95]
	ds_read_b128 v[2:5], v0 offset:192
	ds_read_b128 v[6:9], v0 offset:224
	s_waitcnt lgkmcnt(1)
	v_mfma_f32_32x32x16_bf16 v[80:95], v[2:5], v[116:119], v[80:95]
	s_waitcnt lgkmcnt(0)
	v_mfma_f32_32x32x16_bf16 v[80:95], v[6:9], v[120:123], v[80:95]
	ds_read_b128 v[2:5], v0 offset:256
	ds_read_b128 v[6:9], v0 offset:288
	s_waitcnt lgkmcnt(1)
	v_mfma_f32_32x32x16_bf16 v[80:95], v[2:5], v[124:127], v[80:95]
	s_waitcnt lgkmcnt(0)
	v_mfma_f32_32x32x16_bf16 v[80:95], v[6:9], v[128:131], v[80:95]
	ds_read_b128 v[2:5], v0 offset:320
	ds_read_b128 v[6:9], v0 offset:352
	s_waitcnt lgkmcnt(1)
	v_mfma_f32_32x32x16_bf16 v[80:95], v[2:5], v[132:135], v[80:95]
	s_waitcnt lgkmcnt(0)
	v_mfma_f32_32x32x16_bf16 v[80:95], v[6:9], v[140:143], v[80:95]
	s_nop 11
	v_max_f32_e32 v0, v81, v81
	v_max_f32_e32 v2, v80, v80
	v_max_f32_e32 v0, v2, v0
	v_max3_f32 v0, v0, v82, v83
	v_max3_f32 v0, v0, v84, v85
	v_max3_f32 v0, v0, v86, v87
	v_max3_f32 v0, v0, v88, v89
	v_max3_f32 v0, v0, v90, v91
	v_max3_f32 v0, v0, v92, v93
	v_max3_f32 v0, v0, v94, v95
	ds_bpermute_b32 v2, v209, v0
	s_waitcnt lgkmcnt(0)
	v_max_f32_e32 v2, v2, v2
	v_max_f32_e32 v0, v0, v2
	v_mul_f32_e32 v0, 0x3dd53b94, v0
	v_add_f32_e32 v250, 0xc1000000, v0
	v_cmp_gt_f32_e32 vcc, v250, v198
	s_cbranch_vccz .LBB0_684
	v_max_f32_e32 v0, v0, v0
	v_max_f32_e32 v2, v198, v198
	v_max_f32_e32 v2, v2, v0
	v_sub_f32_e32 v0, v198, v2
	v_exp_f32_e32 v0, v0
	v_mov_b32_e32 v198, v2
	v_pk_mul_f32 v[78:79], v[78:79], v[0:1] op_sel_hi:[1,0]
	v_pk_mul_f32 v[76:77], v[76:77], v[0:1] op_sel_hi:[1,0]
	v_pk_mul_f32 v[74:75], v[74:75], v[0:1] op_sel_hi:[1,0]
	v_pk_mul_f32 v[72:73], v[72:73], v[0:1] op_sel_hi:[1,0]
	v_pk_mul_f32 v[70:71], v[70:71], v[0:1] op_sel_hi:[1,0]
	v_pk_mul_f32 v[68:69], v[68:69], v[0:1] op_sel_hi:[1,0]
	v_pk_mul_f32 v[66:67], v[66:67], v[0:1] op_sel_hi:[1,0]
	v_pk_mul_f32 v[64:65], v[64:65], v[0:1] op_sel_hi:[1,0]
	v_pk_mul_f32 v[62:63], v[62:63], v[0:1] op_sel_hi:[1,0]
	v_pk_mul_f32 v[60:61], v[60:61], v[0:1] op_sel_hi:[1,0]
	v_pk_mul_f32 v[58:59], v[58:59], v[0:1] op_sel_hi:[1,0]
	v_pk_mul_f32 v[56:57], v[56:57], v[0:1] op_sel_hi:[1,0]
	v_pk_mul_f32 v[54:55], v[54:55], v[0:1] op_sel_hi:[1,0]
	v_pk_mul_f32 v[52:53], v[52:53], v[0:1] op_sel_hi:[1,0]
	v_pk_mul_f32 v[50:51], v[50:51], v[0:1] op_sel_hi:[1,0]
	v_pk_mul_f32 v[48:49], v[48:49], v[0:1] op_sel_hi:[1,0]
	v_pk_mul_f32 v[46:47], v[46:47], v[0:1] op_sel_hi:[1,0]
	v_pk_mul_f32 v[44:45], v[44:45], v[0:1] op_sel_hi:[1,0]
	v_pk_mul_f32 v[42:43], v[42:43], v[0:1] op_sel_hi:[1,0]
	v_pk_mul_f32 v[40:41], v[40:41], v[0:1] op_sel_hi:[1,0]
	v_pk_mul_f32 v[38:39], v[38:39], v[0:1] op_sel_hi:[1,0]
	v_pk_mul_f32 v[36:37], v[36:37], v[0:1] op_sel_hi:[1,0]
	v_pk_mul_f32 v[34:35], v[34:35], v[0:1] op_sel_hi:[1,0]
	v_pk_mul_f32 v[32:33], v[32:33], v[0:1] op_sel_hi:[1,0]
	v_pk_mul_f32 v[30:31], v[30:31], v[0:1] op_sel_hi:[1,0]
	v_pk_mul_f32 v[28:29], v[28:29], v[0:1] op_sel_hi:[1,0]
	v_pk_mul_f32 v[26:27], v[26:27], v[0:1] op_sel_hi:[1,0]
	v_pk_mul_f32 v[24:25], v[24:25], v[0:1] op_sel_hi:[1,0]
	v_pk_mul_f32 v[22:23], v[22:23], v[0:1] op_sel_hi:[1,0]
	v_pk_mul_f32 v[20:21], v[20:21], v[0:1] op_sel_hi:[1,0]
	v_pk_mul_f32 v[18:19], v[18:19], v[0:1] op_sel_hi:[1,0]
	v_pk_mul_f32 v[16:17], v[16:17], v[0:1] op_sel_hi:[1,0]
	v_mul_f32_e32 v193, v193, v0
	s_branch .LBB0_684

.LBB0_1022:
	ds_read_b128 v[2:5], v193
	ds_read_b128 v[6:9], v193 offset:32
	s_waitcnt lgkmcnt(1)
	v_mfma_f32_32x32x16_bf16 v[80:95], v[2:5], v[96:99], 0
	s_waitcnt lgkmcnt(0)
	v_mfma_f32_32x32x16_bf16 v[80:95], v[6:9], v[100:103], v[80:95]
	ds_read_b128 v[2:5], v193 offset:64
	ds_read_b128 v[6:9], v193 offset:96
	s_waitcnt lgkmcnt(1)
	v_mfma_f32_32x32x16_bf16 v[80:95], v[2:5], v[104:107], v[80:95]
	s_waitcnt lgkmcnt(0)
	v_mfma_f32_32x32x16_bf16 v[80:95], v[6:9], v[108:111], v[80:95]
	s_nop 11
	v_max_f32_e32 v1, v81, v81
	v_max_f32_e32 v2, v80, v80
	v_max_f32_e32 v1, v2, v1
	v_max3_f32 v1, v1, v82, v83
	v_max3_f32 v1, v1, v84, v85
	v_max3_f32 v1, v1, v86, v87
	v_max3_f32 v1, v1, v88, v89
	v_max3_f32 v1, v1, v90, v91
	v_max3_f32 v1, v1, v92, v93
	v_max3_f32 v1, v1, v94, v95
	ds_bpermute_b32 v2, v184, v1
	s_waitcnt lgkmcnt(0)
	v_max_f32_e32 v2, v2, v2
	v_max_f32_e32 v1, v1, v2
	v_mul_f32_e32 v1, 0x3e38aa3b, v1
	v_add_f32_e32 v250, 0xc1000000, v1
	v_cmp_gt_f32_e32 vcc, v250, v180
	s_cbranch_vccz .LBB0_1024
	v_max_f32_e32 v1, v1, v1
	v_max_f32_e32 v2, v180, v180
	v_max_f32_e32 v1, v2, v1
	v_sub_f32_e32 v2, v180, v1
	v_exp_f32_e32 v2, v2
	v_mov_b32_e32 v180, v1
	v_pk_mul_f32 v[78:79], v[78:79], v[2:3] op_sel_hi:[1,0]
	v_pk_mul_f32 v[76:77], v[76:77], v[2:3] op_sel_hi:[1,0]
	v_pk_mul_f32 v[74:75], v[74:75], v[2:3] op_sel_hi:[1,0]
	v_pk_mul_f32 v[72:73], v[72:73], v[2:3] op_sel_hi:[1,0]
	v_pk_mul_f32 v[70:71], v[70:71], v[2:3] op_sel_hi:[1,0]
	v_pk_mul_f32 v[68:69], v[68:69], v[2:3] op_sel_hi:[1,0]
	v_pk_mul_f32 v[66:67], v[66:67], v[2:3] op_sel_hi:[1,0]
	v_pk_mul_f32 v[64:65], v[64:65], v[2:3] op_sel_hi:[1,0]
	v_pk_mul_f32 v[62:63], v[62:63], v[2:3] op_sel_hi:[1,0]
	v_pk_mul_f32 v[60:61], v[60:61], v[2:3] op_sel_hi:[1,0]
	v_pk_mul_f32 v[58:59], v[58:59], v[2:3] op_sel_hi:[1,0]
	v_pk_mul_f32 v[56:57], v[56:57], v[2:3] op_sel_hi:[1,0]
	v_pk_mul_f32 v[54:55], v[54:55], v[2:3] op_sel_hi:[1,0]
	v_pk_mul_f32 v[52:53], v[52:53], v[2:3] op_sel_hi:[1,0]
	v_pk_mul_f32 v[50:51], v[50:51], v[2:3] op_sel_hi:[1,0]
	v_pk_mul_f32 v[48:49], v[48:49], v[2:3] op_sel_hi:[1,0]
	v_pk_mul_f32 v[46:47], v[46:47], v[2:3] op_sel_hi:[1,0]
	v_pk_mul_f32 v[44:45], v[44:45], v[2:3] op_sel_hi:[1,0]
	v_pk_mul_f32 v[42:43], v[42:43], v[2:3] op_sel_hi:[1,0]
	v_pk_mul_f32 v[40:41], v[40:41], v[2:3] op_sel_hi:[1,0]
	v_pk_mul_f32 v[38:39], v[38:39], v[2:3] op_sel_hi:[1,0]
	v_pk_mul_f32 v[36:37], v[36:37], v[2:3] op_sel_hi:[1,0]
	v_pk_mul_f32 v[34:35], v[34:35], v[2:3] op_sel_hi:[1,0]
	v_pk_mul_f32 v[32:33], v[32:33], v[2:3] op_sel_hi:[1,0]
	v_pk_mul_f32 v[30:31], v[30:31], v[2:3] op_sel_hi:[1,0]
	v_pk_mul_f32 v[28:29], v[28:29], v[2:3] op_sel_hi:[1,0]
	v_pk_mul_f32 v[26:27], v[26:27], v[2:3] op_sel_hi:[1,0]
	v_pk_mul_f32 v[24:25], v[24:25], v[2:3] op_sel_hi:[1,0]
	v_pk_mul_f32 v[22:23], v[22:23], v[2:3] op_sel_hi:[1,0]
	v_pk_mul_f32 v[20:21], v[20:21], v[2:3] op_sel_hi:[1,0]
	v_pk_mul_f32 v[18:19], v[18:19], v[2:3] op_sel_hi:[1,0]
	v_pk_mul_f32 v[16:17], v[16:17], v[2:3] op_sel_hi:[1,0]
	v_mul_f32_e32 v196, v196, v2
.LBB0_1024:
	v_pk_fma_f32 v[2:3], v[80:81], s[18:19], v[180:181] op_sel_hi:[1,0,0] neg_lo:[0,0,1] neg_hi:[0,0,1]
	v_pk_fma_f32 v[6:7], v[86:87], s[18:19], v[180:181] op_sel_hi:[1,0,0] neg_lo:[0,0,1] neg_hi:[0,0,1]
	v_exp_f32_e32 v214, v2
	v_exp_f32_e32 v215, v3
	v_pk_fma_f32 v[2:3], v[82:83], s[18:19], v[180:181] op_sel_hi:[1,0,0] neg_lo:[0,0,1] neg_hi:[0,0,1]
	v_exp_f32_e32 v220, v6
	v_exp_f32_e32 v216, v2
	v_exp_f32_e32 v217, v3
	v_pk_fma_f32 v[2:3], v[84:85], s[18:19], v[180:181] op_sel_hi:[1,0,0] neg_lo:[0,0,1] neg_hi:[0,0,1]
	v_exp_f32_e32 v221, v7
	v_exp_f32_e32 v218, v2
	v_exp_f32_e32 v219, v3
	ds_read_b128 v[2:5], v194 offset:9216
	ds_read_b128 v[10:13], v194 offset:9248
	v_cvt_pk_bf16_f32 v6, v214, v215
	v_cvt_pk_bf16_f32 v7, v216, v217
	v_cvt_pk_bf16_f32 v8, v218, v219
	v_cvt_pk_bf16_f32 v9, v220, v221
	v_pk_fma_f32 v[14:15], v[88:89], s[18:19], v[180:181] op_sel_hi:[1,0,0] neg_lo:[0,0,1] neg_hi:[0,0,1]
	s_waitcnt lgkmcnt(1)
	v_mfma_f32_32x32x16_bf16 v[64:79], v[2:5], v[6:9], v[64:79]
	ds_read_b128 v[2:5], v194 offset:13824
	ds_read_b128 v[202:205], v194 offset:13856
	v_exp_f32_e32 v222, v14
	v_exp_f32_e32 v223, v15
	s_waitcnt lgkmcnt(1)
	v_mfma_f32_32x32x16_bf16 v[48:63], v[2:5], v[6:9], v[48:63]
	ds_read_b128 v[2:5], v194 offset:18432
	ds_read_b128 v[80:83], v194 offset:23040
	ds_read_b128 v[206:209], v194 offset:18464
	ds_read_b128 v[210:213], v194 offset:23072
	s_waitcnt lgkmcnt(3)
	v_mfma_f32_32x32x16_bf16 v[32:47], v[2:5], v[6:9], v[32:47]
	v_fma_f32 v4, v92, s18, -v180
	v_fma_f32 v5, v93, s18, -v180
	v_fma_f32 v2, v90, s18, -v180
	v_fma_f32 v3, v91, s18, -v180
	v_exp_f32_e32 v224, v4
	v_exp_f32_e32 v225, v5
	v_pk_fma_f32 v[4:5], v[94:95], s[18:19], v[180:181] op_sel_hi:[1,0,0] neg_lo:[0,0,1] neg_hi:[0,0,1]
	v_exp_f32_e32 v2, v2
	v_exp_f32_e32 v3, v3
	v_exp_f32_e32 v226, v4
	v_exp_f32_e32 v227, v5
	s_waitcnt lgkmcnt(2)
	v_mfma_f32_32x32x16_bf16 v[16:31], v[80:83], v[6:9], v[16:31]
	v_cvt_pk_bf16_f32 v4, v222, v223
	v_cvt_pk_bf16_f32 v5, v2, v3
	v_cvt_pk_bf16_f32 v6, v224, v225
	v_cvt_pk_bf16_f32 v7, v226, v227
	s_nop 1
	v_mfma_f32_32x32x16_bf16 v[64:79], v[10:13], v[4:7], v[64:79]
	ds_read_b128 v[8:11], v193 offset:4608
	ds_read_b128 v[12:15], v193 offset:4640
	s_waitcnt lgkmcnt(1)
	v_mfma_f32_32x32x16_bf16 v[80:95], v[8:11], v[96:99], 0
	s_waitcnt lgkmcnt(0)
	v_mfma_f32_32x32x16_bf16 v[80:95], v[12:15], v[100:103], v[80:95]
	ds_read_b128 v[8:11], v193 offset:4672
	ds_read_b128 v[12:15], v193 offset:4704
	s_waitcnt lgkmcnt(1)
	v_mfma_f32_32x32x16_bf16 v[80:95], v[8:11], v[104:107], v[80:95]
	v_add_f32_e64 v8, v214, 0
	v_add_f32_e64 v9, v215, 0
	v_add_f32_e64 v8, v216, v8
	v_add_f32_e64 v9, v217, v9
	v_add_f32_e64 v8, v218, v8
	v_add_f32_e64 v9, v219, v9
	v_pk_add_f32 v[8:9], v[220:221], v[8:9]
	s_waitcnt lgkmcnt(0)
	v_mfma_f32_32x32x16_bf16 v[80:95], v[12:15], v[108:111], v[80:95]
	v_add_f32_e64 v8, v222, v8
	v_add_f32_e64 v9, v223, v9
	v_add_f32_e64 v2, v2, v8
	v_add_f32_e64 v3, v3, v9
	v_add_f32_e64 v2, v224, v2
	v_add_f32_e64 v3, v225, v3
	s_nop 5
	v_max_f32_e32 v1, v81, v81
	v_max_f32_e32 v8, v80, v80
	v_max_f32_e32 v1, v8, v1
	v_max3_f32 v1, v1, v82, v83
	v_max3_f32 v1, v1, v84, v85
	v_max3_f32 v1, v1, v86, v87
	v_max3_f32 v1, v1, v88, v89
	v_max3_f32 v1, v1, v90, v91
	v_max3_f32 v1, v1, v92, v93
	v_max3_f32 v8, v1, v94, v95
	ds_bpermute_b32 v9, v184, v8
	v_mfma_f32_32x32x16_bf16 v[48:63], v[202:205], v[4:7], v[48:63]
	v_add_f32_e64 v2, v226, v2
	v_add_f32_e64 v3, v227, v3
	v_add_f32_e32 v1, v2, v3
	s_waitcnt lgkmcnt(0)
	v_max_f32_e32 v2, v9, v9
	v_max_f32_e32 v2, v8, v2
	v_mul_f32_e32 v2, 0x3e38aa3b, v2
	v_add_f32_e32 v1, v196, v1
	v_mfma_f32_32x32x16_bf16 v[32:47], v[206:209], v[4:7], v[32:47]
	v_add_f32_e32 v250, 0xc1000000, v2
	v_cmp_gt_f32_e32 vcc, v250, v180
	v_mfma_f32_32x32x16_bf16 v[16:31], v[210:213], v[4:7], v[16:31]
	s_cbranch_vccnz .LBB0_1018
	v_mov_b64_e32 v[2:3], v[180:181]
	s_branch .LBB0_1019

.LBB0_1297:
	s_barrier
	s_waitcnt vmcnt(3)
	ds_write_b128 v166, v[112:115]
	s_waitcnt vmcnt(2)
	ds_write_b128 v166, v[116:119] offset:4352
	s_waitcnt vmcnt(1)
	ds_write_b128 v166, v[120:123] offset:8704
	s_waitcnt vmcnt(0)
	ds_write_b128 v166, v[124:127] offset:13056
	s_waitcnt vmcnt(1)
	ds_write_b128 v167, v[140:143] offset:17408
	ds_write_b128 v167, v[132:135] offset:22016
	ds_write_b128 v167, v[128:131] offset:26624
	s_waitcnt vmcnt(0)
	ds_write_b128 v167, v[136:139] offset:31232
	s_waitcnt lgkmcnt(0)
	s_barrier
	ds_read_b128 v[64:67], v170
	ds_read_b128 v[112:115], v170 offset:32
	s_waitcnt lgkmcnt(1)
	v_mfma_f32_32x32x16_bf16 v[64:79], v[64:67], v[108:111], 0
	v_lshl_add_u64 v[124:125], s[14:15], 0, v[162:163]
	v_add_co_u32_e32 v178, vcc, s37, v124
	v_lshl_add_u64 v[126:127], s[14:15], 0, v[154:155]
	s_nop 0
	v_addc_co_u32_e32 v179, vcc, 0, v125, vcc
	v_add_co_u32_e32 v180, vcc, s38, v124
	s_waitcnt lgkmcnt(0)
	v_mfma_f32_32x32x16_bf16 v[64:79], v[112:115], v[104:107], v[64:79]
	ds_read_b128 v[112:115], v170 offset:64
	ds_read_b128 v[116:119], v170 offset:96
	v_lshl_add_u64 v[128:129], s[14:15], 0, v[156:157]
	v_lshl_add_u64 v[130:131], s[14:15], 0, v[158:159]
	v_lshl_add_u64 v[136:137], s[14:15], 0, v[160:161]
	v_addc_co_u32_e32 v181, vcc, 0, v125, vcc
	v_add_co_u32_e32 v182, vcc, s39, v124
	s_waitcnt lgkmcnt(1)
	v_mfma_f32_32x32x16_bf16 v[64:79], v[112:115], v[100:103], v[64:79]
	ds_read_b128 v[112:115], v170 offset:128
	v_addc_co_u32_e32 v183, vcc, 0, v125, vcc
	v_add_co_u32_e32 v124, vcc, s40, v124
	s_nop 1
	v_addc_co_u32_e32 v125, vcc, 0, v125, vcc
	s_waitcnt lgkmcnt(1)
	v_mfma_f32_32x32x16_bf16 v[64:79], v[116:119], v[96:99], v[64:79]
	ds_read_b128 v[116:119], v170 offset:160
	ds_read_b128 v[120:123], v170 offset:192
	ds_read_b128 v[174:177], v170 offset:224
	s_waitcnt lgkmcnt(3)
	v_mfma_f32_32x32x16_bf16 v[64:79], v[112:115], v[92:95], v[64:79]
	s_waitcnt lgkmcnt(2)
	v_mfma_f32_32x32x16_bf16 v[64:79], v[116:119], v[88:91], v[64:79]
	global_load_dwordx4 v[140:143], v[126:127], off
	global_load_dwordx4 v[132:135], v[128:129], off
	s_nop 0
	global_load_dwordx4 v[128:131], v[130:131], off
	s_nop 0
	global_load_dwordx4 v[136:139], v[136:137], off
	s_nop 0
	global_load_dwordx4 v[112:115], v[178:179], off
	global_load_dwordx4 v[116:119], v[180:181], off
	s_waitcnt lgkmcnt(1)
	v_mfma_f32_32x32x16_bf16 v[64:79], v[120:123], v[84:87], v[64:79]
	global_load_dwordx4 v[120:123], v[182:183], off
	s_nop 0
	global_load_dwordx4 v[124:127], v[124:125], off
	s_waitcnt lgkmcnt(0)
	v_mfma_f32_32x32x16_bf16 v[64:79], v[174:177], v[80:83], v[64:79]
	s_nop 11
	v_max_f32_e32 v152, v65, v65
	v_max_f32_e32 v173, v64, v64
	v_max_f32_e32 v152, v173, v152
	v_max3_f32 v152, v152, v66, v67
	v_max3_f32 v152, v152, v68, v69
	v_max3_f32 v152, v152, v70, v71
	v_max3_f32 v152, v152, v72, v73
	v_max3_f32 v152, v152, v74, v75
	v_max3_f32 v152, v152, v76, v77
	v_max3_f32 v152, v152, v78, v79
	ds_bpermute_b32 v173, v168, v152
	s_waitcnt lgkmcnt(0)
	v_max_f32_e32 v173, v173, v173
	v_max_f32_e32 v152, v152, v173
	v_mul_f32_e32 v152, 0x3e0293ee, v152
	v_add_f32_e32 v250, 0xc1000000, v152
	v_cmp_gt_f32_e32 vcc, v250, v153
	s_cbranch_vccz .LBB0_1299
	v_max_f32_e32 v152, v152, v152
	v_max_f32_e32 v173, v153, v153
	v_max_f32_e32 v173, v173, v152
	v_sub_f32_e32 v152, v153, v173
	v_exp_f32_e32 v152, v152
	s_nop 0
	v_pk_mul_f32 v[62:63], v[62:63], v[152:153] op_sel_hi:[1,0]
	v_pk_mul_f32 v[60:61], v[60:61], v[152:153] op_sel_hi:[1,0]
	v_pk_mul_f32 v[58:59], v[58:59], v[152:153] op_sel_hi:[1,0]
	v_pk_mul_f32 v[56:57], v[56:57], v[152:153] op_sel_hi:[1,0]
	v_pk_mul_f32 v[54:55], v[54:55], v[152:153] op_sel_hi:[1,0]
	v_pk_mul_f32 v[52:53], v[52:53], v[152:153] op_sel_hi:[1,0]
	v_pk_mul_f32 v[50:51], v[50:51], v[152:153] op_sel_hi:[1,0]
	v_pk_mul_f32 v[48:49], v[48:49], v[152:153] op_sel_hi:[1,0]
	v_pk_mul_f32 v[46:47], v[46:47], v[152:153] op_sel_hi:[1,0]
	v_pk_mul_f32 v[44:45], v[44:45], v[152:153] op_sel_hi:[1,0]
	v_pk_mul_f32 v[42:43], v[42:43], v[152:153] op_sel_hi:[1,0]
	v_pk_mul_f32 v[40:41], v[40:41], v[152:153] op_sel_hi:[1,0]
	v_pk_mul_f32 v[38:39], v[38:39], v[152:153] op_sel_hi:[1,0]
	v_pk_mul_f32 v[36:37], v[36:37], v[152:153] op_sel_hi:[1,0]
	v_pk_mul_f32 v[34:35], v[34:35], v[152:153] op_sel_hi:[1,0]
	v_pk_mul_f32 v[32:33], v[32:33], v[152:153] op_sel_hi:[1,0]
	v_pk_mul_f32 v[30:31], v[30:31], v[152:153] op_sel_hi:[1,0]
	v_pk_mul_f32 v[28:29], v[28:29], v[152:153] op_sel_hi:[1,0]
	v_pk_mul_f32 v[26:27], v[26:27], v[152:153] op_sel_hi:[1,0]
	v_pk_mul_f32 v[24:25], v[24:25], v[152:153] op_sel_hi:[1,0]
	v_pk_mul_f32 v[22:23], v[22:23], v[152:153] op_sel_hi:[1,0]
	v_pk_mul_f32 v[20:21], v[20:21], v[152:153] op_sel_hi:[1,0]
	v_pk_mul_f32 v[18:19], v[18:19], v[152:153] op_sel_hi:[1,0]
	v_pk_mul_f32 v[16:17], v[16:17], v[152:153] op_sel_hi:[1,0]
	v_pk_mul_f32 v[14:15], v[14:15], v[152:153] op_sel_hi:[1,0]
	v_pk_mul_f32 v[12:13], v[12:13], v[152:153] op_sel_hi:[1,0]
	v_pk_mul_f32 v[10:11], v[10:11], v[152:153] op_sel_hi:[1,0]
	v_pk_mul_f32 v[8:9], v[8:9], v[152:153] op_sel_hi:[1,0]
	v_pk_mul_f32 v[6:7], v[6:7], v[152:153] op_sel_hi:[1,0]
	v_pk_mul_f32 v[4:5], v[4:5], v[152:153] op_sel_hi:[1,0]
	v_pk_mul_f32 v[2:3], v[2:3], v[152:153] op_sel_hi:[1,0]
	v_pk_mul_f32 v[0:1], v[0:1], v[152:153] op_sel_hi:[1,0]
	v_mul_f32_e32 v172, v172, v152
	v_mov_b32_e32 v153, v173
.LBB0_1299:
	v_mov_b32_e32 v152, v153
	v_pk_fma_f32 v[64:65], v[64:65], s[18:19], v[152:153] op_sel_hi:[1,0,0] neg_lo:[0,0,1] neg_hi:[0,0,1]
	v_pk_fma_f32 v[72:73], v[72:73], s[18:19], v[152:153] op_sel_hi:[1,0,0] neg_lo:[0,0,1] neg_hi:[0,0,1]
	v_exp_f32_e32 v202, v64
	v_exp_f32_e32 v203, v65
	v_pk_fma_f32 v[64:65], v[66:67], s[18:19], v[152:153] op_sel_hi:[1,0,0] neg_lo:[0,0,1] neg_hi:[0,0,1]
	ds_read_b128 v[174:177], v171 offset:17440
	v_exp_f32_e32 v204, v64
	v_exp_f32_e32 v205, v65
	v_pk_fma_f32 v[64:65], v[68:69], s[18:19], v[152:153] op_sel_hi:[1,0,0] neg_lo:[0,0,1] neg_hi:[0,0,1]
	v_pk_fma_f32 v[68:69], v[70:71], s[18:19], v[152:153] op_sel_hi:[1,0,0] neg_lo:[0,0,1] neg_hi:[0,0,1]
	v_exp_f32_e32 v206, v64
	v_exp_f32_e32 v207, v65
	ds_read_b128 v[64:67], v171 offset:17408
	v_exp_f32_e32 v208, v68
	v_exp_f32_e32 v209, v69
	v_cvt_pk_bf16_f32 v68, v202, v203
	v_cvt_pk_bf16_f32 v69, v204, v205
	v_cvt_pk_bf16_f32 v70, v206, v207
	v_cvt_pk_bf16_f32 v71, v208, v209
	v_exp_f32_e32 v210, v72
	v_exp_f32_e32 v211, v73
	s_waitcnt lgkmcnt(0)
	v_mfma_f32_32x32x16_bf16 v[48:63], v[64:67], v[68:71], v[48:63]
	ds_read_b128 v[64:67], v171 offset:22016
	ds_read_b128 v[178:181], v171 offset:22048
	s_waitcnt lgkmcnt(1)
	v_mfma_f32_32x32x16_bf16 v[32:47], v[64:67], v[68:71], v[32:47]
	ds_read_b128 v[64:67], v171 offset:26624
	ds_read_b128 v[182:185], v171 offset:31232
	ds_read_b128 v[186:189], v171 offset:26656
	ds_read_b128 v[190:193], v171 offset:31264
	s_waitcnt lgkmcnt(3)
	v_mfma_f32_32x32x16_bf16 v[16:31], v[64:67], v[68:71], v[16:31]
	v_fma_f32 v64, v74, s18, -v152
	v_fma_f32 v65, v75, s18, -v152
	v_exp_f32_e32 v212, v64
	v_exp_f32_e32 v213, v65
	v_pk_fma_f32 v[64:65], v[76:77], s[18:19], v[152:153] op_sel_hi:[1,0,0] neg_lo:[0,0,1] neg_hi:[0,0,1]
	s_nop 0
	v_exp_f32_e32 v214, v64
	v_exp_f32_e32 v215, v65
	v_pk_fma_f32 v[64:65], v[78:79], s[18:19], v[152:153] op_sel_hi:[1,0,0] neg_lo:[0,0,1] neg_hi:[0,0,1]
	s_waitcnt lgkmcnt(2)
	v_mfma_f32_32x32x16_bf16 v[0:15], v[182:185], v[68:71], v[0:15]
	v_exp_f32_e32 v216, v64
	v_exp_f32_e32 v217, v65
	v_cvt_pk_bf16_f32 v182, v210, v211
	v_cvt_pk_bf16_f32 v183, v212, v213
	v_cvt_pk_bf16_f32 v184, v214, v215
	v_cvt_pk_bf16_f32 v185, v216, v217
	s_nop 1
	v_mfma_f32_32x32x16_bf16 v[48:63], v[174:177], v[182:185], v[48:63]
	ds_read_b128 v[64:67], v170 offset:8704
	ds_read_b128 v[174:177], v170 offset:8736
	s_waitcnt lgkmcnt(1)
	v_mfma_f32_32x32x16_bf16 v[64:79], v[64:67], v[108:111], 0
	s_waitcnt lgkmcnt(0)
	v_mfma_f32_32x32x16_bf16 v[64:79], v[174:177], v[104:107], v[64:79]
	ds_read_b128 v[174:177], v170 offset:8768
	ds_read_b128 v[194:197], v170 offset:8800
	s_waitcnt lgkmcnt(1)
	v_mfma_f32_32x32x16_bf16 v[64:79], v[174:177], v[100:103], v[64:79]
	s_waitcnt lgkmcnt(0)
	v_mfma_f32_32x32x16_bf16 v[64:79], v[194:197], v[96:99], v[64:79]
	ds_read_b128 v[174:177], v170 offset:8832
	ds_read_b128 v[194:197], v170 offset:8864
	s_waitcnt lgkmcnt(1)
	v_mfma_f32_32x32x16_bf16 v[64:79], v[174:177], v[92:95], v[64:79]
	s_waitcnt lgkmcnt(0)
	v_mfma_f32_32x32x16_bf16 v[64:79], v[194:197], v[88:91], v[64:79]
	ds_read_b128 v[174:177], v170 offset:8896
	ds_read_b128 v[194:197], v170 offset:8928
	s_waitcnt lgkmcnt(1)
	v_mfma_f32_32x32x16_bf16 v[64:79], v[174:177], v[84:87], v[64:79]
	v_add_f32_e64 v174, v202, 0
	v_add_f32_e64 v175, v203, 0
	v_add_f32_e64 v174, v204, v174
	v_add_f32_e64 v175, v205, v175
	v_add_f32_e64 v174, v206, v174
	v_add_f32_e64 v175, v207, v175
	v_pk_add_f32 v[174:175], v[208:209], v[174:175]
	s_waitcnt lgkmcnt(0)
	v_mfma_f32_32x32x16_bf16 v[64:79], v[194:197], v[80:83], v[64:79]
	v_add_f32_e64 v174, v210, v174
	v_add_f32_e64 v175, v211, v175
	v_add_f32_e64 v174, v212, v174
	v_add_f32_e64 v175, v213, v175
	v_add_f32_e64 v174, v214, v174
	v_add_f32_e64 v175, v215, v175
	s_nop 5
	v_max_f32_e32 v152, v65, v65
	v_max_f32_e32 v173, v64, v64
	v_max_f32_e32 v152, v173, v152
	v_max3_f32 v152, v152, v66, v67
	v_max3_f32 v152, v152, v68, v69
	v_max3_f32 v152, v152, v70, v71
	v_max3_f32 v152, v152, v72, v73
	v_max3_f32 v152, v152, v74, v75
	v_max3_f32 v152, v152, v76, v77
	v_max3_f32 v152, v152, v78, v79
	ds_bpermute_b32 v173, v168, v152
	v_mfma_f32_32x32x16_bf16 v[32:47], v[178:181], v[182:185], v[32:47]
	v_add_f32_e64 v174, v216, v174
	v_add_f32_e64 v175, v217, v175
	s_waitcnt lgkmcnt(0)
	v_max_f32_e32 v173, v173, v173
	v_max_f32_e32 v152, v152, v173
	v_add_f32_e32 v174, v174, v175
	v_mul_f32_e32 v152, 0x3e0293ee, v152
	v_mfma_f32_32x32x16_bf16 v[16:31], v[186:189], v[182:185], v[16:31]
	v_add_f32_e32 v172, v172, v174
	v_add_f32_e32 v250, 0xc1000000, v152
	v_cmp_gt_f32_e32 vcc, v250, v153
	v_mfma_f32_32x32x16_bf16 v[0:15], v[190:193], v[182:185], v[0:15]
	s_cbranch_vccnz .LBB0_1295
	v_mov_b32_e32 v152, v153
	s_branch .LBB0_1296
.LBB0_1301:
	s_barrier
	s_waitcnt vmcnt(3)
	ds_write_b128 v166, v[112:115]
	s_waitcnt vmcnt(2)
	ds_write_b128 v166, v[116:119] offset:4352
	s_waitcnt vmcnt(1)
	ds_write_b128 v166, v[120:123] offset:8704
	s_waitcnt vmcnt(0)
	ds_write_b128 v166, v[124:127] offset:13056
	ds_write_b128 v167, v[140:143] offset:17408
	ds_write_b128 v167, v[132:135] offset:22016
	ds_write_b128 v167, v[128:131] offset:26624
	ds_write_b128 v167, v[136:139] offset:31232
	s_waitcnt lgkmcnt(0)
	s_barrier
	ds_read_b128 v[64:67], v170
	ds_read_b128 v[112:115], v170 offset:32
	s_waitcnt lgkmcnt(1)
	v_mfma_f32_32x32x16_bf16 v[64:79], v[64:67], v[108:111], 0
	s_waitcnt lgkmcnt(0)
	v_mfma_f32_32x32x16_bf16 v[64:79], v[112:115], v[104:107], v[64:79]
	ds_read_b128 v[112:115], v170 offset:64
	ds_read_b128 v[116:119], v170 offset:96
	s_waitcnt lgkmcnt(1)
	v_mfma_f32_32x32x16_bf16 v[64:79], v[112:115], v[100:103], v[64:79]
	s_waitcnt lgkmcnt(0)
	v_mfma_f32_32x32x16_bf16 v[64:79], v[116:119], v[96:99], v[64:79]
	ds_read_b128 v[112:115], v170 offset:128
	ds_read_b128 v[116:119], v170 offset:160
	s_waitcnt lgkmcnt(1)
	v_mfma_f32_32x32x16_bf16 v[64:79], v[112:115], v[92:95], v[64:79]
	s_waitcnt lgkmcnt(0)
	v_mfma_f32_32x32x16_bf16 v[64:79], v[116:119], v[88:91], v[64:79]
	ds_read_b128 v[112:115], v170 offset:192
	ds_read_b128 v[116:119], v170 offset:224
	s_waitcnt lgkmcnt(1)
	v_mfma_f32_32x32x16_bf16 v[64:79], v[112:115], v[84:87], v[64:79]
	s_waitcnt lgkmcnt(0)
	v_mfma_f32_32x32x16_bf16 v[64:79], v[116:119], v[80:83], v[64:79]
	s_nop 11
	v_max_f32_e32 v112, v65, v65
	v_max_f32_e32 v113, v64, v64
	v_max_f32_e32 v112, v113, v112
	v_max3_f32 v112, v112, v66, v67
	v_max3_f32 v112, v112, v68, v69
	v_max3_f32 v112, v112, v70, v71
	v_max3_f32 v112, v112, v72, v73
	v_max3_f32 v112, v112, v74, v75
	v_max3_f32 v112, v112, v76, v77
	v_max3_f32 v112, v112, v78, v79
	ds_bpermute_b32 v113, v168, v112
	s_waitcnt lgkmcnt(0)
	v_max_f32_e32 v113, v113, v113
	v_max_f32_e32 v112, v112, v113
	v_mul_f32_e32 v112, 0x3e0293ee, v112
	v_add_f32_e32 v250, 0xc1000000, v112
	v_cmp_gt_f32_e32 vcc, v250, v153
	s_cbranch_vccz .LBB0_1303
	v_max_f32_e32 v112, v112, v112
	v_max_f32_e32 v113, v153, v153
	v_max_f32_e32 v152, v113, v112
	v_sub_f32_e32 v112, v153, v152
	v_exp_f32_e32 v112, v112
	v_mov_b32_e32 v153, v152
	v_pk_mul_f32 v[62:63], v[62:63], v[112:113] op_sel_hi:[1,0]
	v_pk_mul_f32 v[60:61], v[60:61], v[112:113] op_sel_hi:[1,0]
	v_pk_mul_f32 v[58:59], v[58:59], v[112:113] op_sel_hi:[1,0]
	v_pk_mul_f32 v[56:57], v[56:57], v[112:113] op_sel_hi:[1,0]
	v_pk_mul_f32 v[54:55], v[54:55], v[112:113] op_sel_hi:[1,0]
	v_pk_mul_f32 v[52:53], v[52:53], v[112:113] op_sel_hi:[1,0]
	v_pk_mul_f32 v[50:51], v[50:51], v[112:113] op_sel_hi:[1,0]
	v_pk_mul_f32 v[48:49], v[48:49], v[112:113] op_sel_hi:[1,0]
	v_pk_mul_f32 v[46:47], v[46:47], v[112:113] op_sel_hi:[1,0]
	v_pk_mul_f32 v[44:45], v[44:45], v[112:113] op_sel_hi:[1,0]
	v_pk_mul_f32 v[42:43], v[42:43], v[112:113] op_sel_hi:[1,0]
	v_pk_mul_f32 v[40:41], v[40:41], v[112:113] op_sel_hi:[1,0]
	v_pk_mul_f32 v[38:39], v[38:39], v[112:113] op_sel_hi:[1,0]
	v_pk_mul_f32 v[36:37], v[36:37], v[112:113] op_sel_hi:[1,0]
	v_pk_mul_f32 v[34:35], v[34:35], v[112:113] op_sel_hi:[1,0]
	v_pk_mul_f32 v[32:33], v[32:33], v[112:113] op_sel_hi:[1,0]
	v_pk_mul_f32 v[30:31], v[30:31], v[112:113] op_sel_hi:[1,0]
	v_pk_mul_f32 v[28:29], v[28:29], v[112:113] op_sel_hi:[1,0]
	v_pk_mul_f32 v[26:27], v[26:27], v[112:113] op_sel_hi:[1,0]
	v_pk_mul_f32 v[24:25], v[24:25], v[112:113] op_sel_hi:[1,0]
	v_pk_mul_f32 v[22:23], v[22:23], v[112:113] op_sel_hi:[1,0]
	v_pk_mul_f32 v[20:21], v[20:21], v[112:113] op_sel_hi:[1,0]
	v_pk_mul_f32 v[18:19], v[18:19], v[112:113] op_sel_hi:[1,0]
	v_pk_mul_f32 v[16:17], v[16:17], v[112:113] op_sel_hi:[1,0]
	v_pk_mul_f32 v[14:15], v[14:15], v[112:113] op_sel_hi:[1,0]
	v_pk_mul_f32 v[12:13], v[12:13], v[112:113] op_sel_hi:[1,0]
	v_pk_mul_f32 v[10:11], v[10:11], v[112:113] op_sel_hi:[1,0]
	v_pk_mul_f32 v[8:9], v[8:9], v[112:113] op_sel_hi:[1,0]
	v_pk_mul_f32 v[6:7], v[6:7], v[112:113] op_sel_hi:[1,0]
	v_pk_mul_f32 v[4:5], v[4:5], v[112:113] op_sel_hi:[1,0]
	v_pk_mul_f32 v[2:3], v[2:3], v[112:113] op_sel_hi:[1,0]
	v_pk_mul_f32 v[0:1], v[0:1], v[112:113] op_sel_hi:[1,0]
	v_mul_f32_e32 v172, v172, v112
	v_mov_b32_e32 v112, v152
	s_branch .LBB0_1304

.LBB0_1304:
	v_pk_fma_f32 v[64:65], v[64:65], s[18:19], v[152:153] op_sel_hi:[1,0,1] neg_lo:[0,0,1] neg_hi:[0,0,1]
	v_pk_fma_f32 v[72:73], v[72:73], s[18:19], v[152:153] op_sel_hi:[1,0,1] neg_lo:[0,0,1] neg_hi:[0,0,1]
	v_exp_f32_e32 v134, v64
	v_exp_f32_e32 v135, v65
	v_pk_fma_f32 v[64:65], v[66:67], s[18:19], v[152:153] op_sel_hi:[1,0,1] neg_lo:[0,0,1] neg_hi:[0,0,1]
	ds_read_b128 v[114:117], v171 offset:17440
	v_exp_f32_e32 v136, v64
	v_exp_f32_e32 v137, v65
	v_pk_fma_f32 v[64:65], v[68:69], s[18:19], v[152:153] op_sel_hi:[1,0,1] neg_lo:[0,0,1] neg_hi:[0,0,1]
	v_pk_fma_f32 v[68:69], v[70:71], s[18:19], v[152:153] op_sel_hi:[1,0,1] neg_lo:[0,0,1] neg_hi:[0,0,1]
	v_exp_f32_e32 v138, v64
	v_exp_f32_e32 v139, v65
	ds_read_b128 v[64:67], v171 offset:17408
	v_exp_f32_e32 v140, v68
	v_exp_f32_e32 v141, v69
	v_cvt_pk_bf16_f32 v68, v134, v135
	v_cvt_pk_bf16_f32 v69, v136, v137
	v_cvt_pk_bf16_f32 v70, v138, v139
	v_cvt_pk_bf16_f32 v71, v140, v141
	v_exp_f32_e32 v142, v72
	v_exp_f32_e32 v143, v73
	s_waitcnt lgkmcnt(0)
	v_mfma_f32_32x32x16_bf16 v[48:63], v[64:67], v[68:71], v[48:63]
	ds_read_b128 v[64:67], v171 offset:22016
	ds_read_b128 v[118:121], v171 offset:22048
	s_waitcnt lgkmcnt(1)
	v_mfma_f32_32x32x16_bf16 v[32:47], v[64:67], v[68:71], v[32:47]
	ds_read_b128 v[64:67], v171 offset:26624
	ds_read_b128 v[122:125], v171 offset:31232
	ds_read_b128 v[126:129], v171 offset:26656
	ds_read_b128 v[130:133], v171 offset:31264
	s_waitcnt lgkmcnt(3)
	v_mfma_f32_32x32x16_bf16 v[16:31], v[64:67], v[68:71], v[16:31]
	v_fma_f32 v64, v74, s18, -v152
	v_fma_f32 v65, v75, s18, -v153
	v_exp_f32_e32 v154, v64
	v_exp_f32_e32 v155, v65
	v_pk_fma_f32 v[64:65], v[76:77], s[18:19], v[152:153] op_sel_hi:[1,0,1] neg_lo:[0,0,1] neg_hi:[0,0,1]
	s_nop 0
	v_exp_f32_e32 v156, v64
	v_exp_f32_e32 v157, v65
	v_pk_fma_f32 v[64:65], v[78:79], s[18:19], v[152:153] op_sel_hi:[1,0,1] neg_lo:[0,0,1] neg_hi:[0,0,1]
	s_waitcnt lgkmcnt(2)
	v_mfma_f32_32x32x16_bf16 v[0:15], v[122:125], v[68:71], v[0:15]
	v_exp_f32_e32 v158, v64
	v_exp_f32_e32 v159, v65
	v_cvt_pk_bf16_f32 v122, v142, v143
	v_cvt_pk_bf16_f32 v123, v154, v155
	v_cvt_pk_bf16_f32 v124, v156, v157
	v_cvt_pk_bf16_f32 v125, v158, v159
	s_nop 1
	v_mfma_f32_32x32x16_bf16 v[48:63], v[114:117], v[122:125], v[48:63]
	ds_read_b128 v[64:67], v170 offset:8704
	ds_read_b128 v[114:117], v170 offset:8736
	s_waitcnt lgkmcnt(1)
	v_mfma_f32_32x32x16_bf16 v[64:79], v[64:67], v[108:111], 0
	s_waitcnt lgkmcnt(0)
	v_mfma_f32_32x32x16_bf16 v[64:79], v[114:117], v[104:107], v[64:79]
	ds_read_b128 v[104:107], v170 offset:8768
	ds_read_b128 v[108:111], v170 offset:8800
	s_waitcnt lgkmcnt(1)
	v_mfma_f32_32x32x16_bf16 v[64:79], v[104:107], v[100:103], v[64:79]
	s_waitcnt lgkmcnt(0)
	v_mfma_f32_32x32x16_bf16 v[64:79], v[108:111], v[96:99], v[64:79]
	ds_read_b128 v[96:99], v170 offset:8832
	ds_read_b128 v[100:103], v170 offset:8864
	s_waitcnt lgkmcnt(1)
	v_mfma_f32_32x32x16_bf16 v[64:79], v[96:99], v[92:95], v[64:79]
	s_waitcnt lgkmcnt(0)
	v_mfma_f32_32x32x16_bf16 v[64:79], v[100:103], v[88:91], v[64:79]
	ds_read_b128 v[88:91], v170 offset:8896
	ds_read_b128 v[92:95], v170 offset:8928
	s_waitcnt lgkmcnt(1)
	v_mfma_f32_32x32x16_bf16 v[64:79], v[88:91], v[84:87], v[64:79]
	v_add_f32_e64 v84, v134, 0
	v_add_f32_e64 v85, v135, 0
	v_add_f32_e64 v84, v136, v84
	v_add_f32_e64 v85, v137, v85
	v_add_f32_e64 v84, v138, v84
	v_add_f32_e64 v85, v139, v85
	v_pk_add_f32 v[84:85], v[140:141], v[84:85]
	s_waitcnt lgkmcnt(0)
	v_mfma_f32_32x32x16_bf16 v[64:79], v[92:95], v[80:83], v[64:79]
	v_add_f32_e64 v80, v142, v84
	v_add_f32_e64 v81, v143, v85
	v_add_f32_e64 v80, v154, v80
	v_add_f32_e64 v81, v155, v81
	v_add_f32_e64 v80, v156, v80
	v_add_f32_e64 v81, v157, v81
	s_nop 5
	v_max_f32_e32 v82, v65, v65
	v_max_f32_e32 v83, v64, v64
	v_max_f32_e32 v82, v83, v82
	v_max3_f32 v82, v82, v66, v67
	v_max3_f32 v82, v82, v68, v69
	v_max3_f32 v82, v82, v70, v71
	v_max3_f32 v82, v82, v72, v73
	v_max3_f32 v82, v82, v74, v75
	v_max3_f32 v82, v82, v76, v77
	v_max3_f32 v82, v82, v78, v79
	ds_bpermute_b32 v83, v168, v82
	v_mfma_f32_32x32x16_bf16 v[32:47], v[118:121], v[122:125], v[32:47]
	v_add_f32_e64 v80, v158, v80
	v_add_f32_e64 v81, v159, v81
	v_add_f32_e32 v80, v80, v81
	s_waitcnt lgkmcnt(0)
	v_max_f32_e32 v81, v83, v83
	v_max_f32_e32 v81, v82, v81
	v_mul_f32_e32 v81, 0x3e0293ee, v81
	v_add_f32_e32 v80, v172, v80
	v_mfma_f32_32x32x16_bf16 v[16:31], v[126:129], v[122:125], v[16:31]
	v_add_f32_e32 v250, 0xc1000000, v81
	v_cmp_gt_f32_e32 vcc, v250, v112
	v_mfma_f32_32x32x16_bf16 v[0:15], v[130:133], v[122:125], v[0:15]
	s_cbranch_vccz .LBB0_1285
	v_max_f32_e32 v81, v81, v81
	v_max_f32_e32 v82, v112, v112
	v_max_f32_e32 v152, v82, v81
	v_sub_f32_e32 v81, v112, v152
	v_exp_f32_e32 v82, v81
	v_mov_b32_e32 v153, v152
	v_pk_mul_f32 v[62:63], v[62:63], v[82:83] op_sel_hi:[1,0]
	v_pk_mul_f32 v[60:61], v[60:61], v[82:83] op_sel_hi:[1,0]
	v_pk_mul_f32 v[58:59], v[58:59], v[82:83] op_sel_hi:[1,0]
	v_pk_mul_f32 v[56:57], v[56:57], v[82:83] op_sel_hi:[1,0]
	v_pk_mul_f32 v[54:55], v[54:55], v[82:83] op_sel_hi:[1,0]
	v_pk_mul_f32 v[52:53], v[52:53], v[82:83] op_sel_hi:[1,0]
	v_pk_mul_f32 v[50:51], v[50:51], v[82:83] op_sel_hi:[1,0]
	v_pk_mul_f32 v[48:49], v[48:49], v[82:83] op_sel_hi:[1,0]
	v_pk_mul_f32 v[46:47], v[46:47], v[82:83] op_sel_hi:[1,0]
	v_pk_mul_f32 v[44:45], v[44:45], v[82:83] op_sel_hi:[1,0]
	v_pk_mul_f32 v[42:43], v[42:43], v[82:83] op_sel_hi:[1,0]
	v_pk_mul_f32 v[40:41], v[40:41], v[82:83] op_sel_hi:[1,0]
	v_pk_mul_f32 v[38:39], v[38:39], v[82:83] op_sel_hi:[1,0]
	v_pk_mul_f32 v[36:37], v[36:37], v[82:83] op_sel_hi:[1,0]
	v_pk_mul_f32 v[34:35], v[34:35], v[82:83] op_sel_hi:[1,0]
	v_pk_mul_f32 v[32:33], v[32:33], v[82:83] op_sel_hi:[1,0]
	v_pk_mul_f32 v[30:31], v[30:31], v[82:83] op_sel_hi:[1,0]
	v_pk_mul_f32 v[28:29], v[28:29], v[82:83] op_sel_hi:[1,0]
	v_pk_mul_f32 v[26:27], v[26:27], v[82:83] op_sel_hi:[1,0]
	v_pk_mul_f32 v[24:25], v[24:25], v[82:83] op_sel_hi:[1,0]
	v_pk_mul_f32 v[22:23], v[22:23], v[82:83] op_sel_hi:[1,0]
	v_pk_mul_f32 v[20:21], v[20:21], v[82:83] op_sel_hi:[1,0]
	v_pk_mul_f32 v[18:19], v[18:19], v[82:83] op_sel_hi:[1,0]
	v_pk_mul_f32 v[16:17], v[16:17], v[82:83] op_sel_hi:[1,0]
	v_pk_mul_f32 v[14:15], v[14:15], v[82:83] op_sel_hi:[1,0]
	v_pk_mul_f32 v[12:13], v[12:13], v[82:83] op_sel_hi:[1,0]
	v_pk_mul_f32 v[10:11], v[10:11], v[82:83] op_sel_hi:[1,0]
	v_pk_mul_f32 v[8:9], v[8:9], v[82:83] op_sel_hi:[1,0]
	v_pk_mul_f32 v[6:7], v[6:7], v[82:83] op_sel_hi:[1,0]
	v_pk_mul_f32 v[4:5], v[4:5], v[82:83] op_sel_hi:[1,0]
	v_pk_mul_f32 v[2:3], v[2:3], v[82:83] op_sel_hi:[1,0]
	v_pk_mul_f32 v[0:1], v[0:1], v[82:83] op_sel_hi:[1,0]
	v_mul_f32_e32 v80, v80, v82
	s_branch .LBB0_1285
